# v61 + stack of the individually validated work-removing edits: MLP1 epilogue with v_pk_mul, trimmed MFMA segments, halves staggered across tiles
# baseline (speedup 1.0000x reference)
; __device__ __forceinline__ unsigned cvt_pk_bf16(float lo, float hi) { unsigned r; asm volatile("v_cvt_pk_bf16_f32 %0, %1, %2" : "=v"(r) : "v"(lo), "v"(hi)); return r; }
; #define PG8_OPQ(p) asm volatile("" : "+v"(p))
;     __device__ __forceinline__ void operator()(const f32x4 (&acc)[2][2][4][2], const Unit& u, int wr, int wc, int fr, int fq) const {
;     ...
;             for (int m = 0; m < 4; ++m) {
;                 PG8_OPQ(p);
; #pragma unroll
;                 for (int bj = 0; bj < 2; ++bj) { f32x4 v0 = acc[ai][bj][m][0], v1 = acc[ai][bj][m][1];
;                     if (ACT == 1) {
; #pragma unroll
;                         for (int j = 0; j < 4; ++j) { const float a0 = fmaxf(v0[j], 0.f), a1 = fmaxf(v1[j], 0.f); v0[j] = a0 * a0; v1[j] = a1 * a1; } }
;                     u32x4 w; w.x = cvt_pk_bf16(v0[0], v0[1]); w.y = cvt_pk_bf16(v0[2], v0[3]); w.z = cvt_pk_bf16(v1[0], v1[1]); w.w = cvt_pk_bf16(v1[2], v1[3]);
;                     *(u32x4*)(p + bj * HALF * 2) = w; }
;                 p += step;
;             }
;             p += 4 * step;
;         }
;     }
.LBB0_438:
	s_lshr_b32 s36, s8, 2
	s_lshl_b32 s36, s36, 23
	s_and_b32 s99, s8, 3
	s_lshl_b32 s99, s99, 8
	s_add_u32 s36, s36, s99
	s_lshr_b32 s99, s98, 14
	s_add_u32 s36, s36, s99
	v_lshl_add_u64 v[144:145], s[36:37], 1, v[136:137]
	v_max3_f32 v122, v122, v122, 0
	v_max3_f32 v123, v123, v123, 0
	v_max3_f32 v124, v124, v124, 0
	v_max3_f32 v125, v125, v125, 0
	v_max3_f32 v126, v126, v126, 0
	v_max3_f32 v127, v127, v127, 0
	v_max3_f32 v128, v128, v128, 0
	v_max3_f32 v129, v129, v129, 0
	v_pk_mul_f32 v[122:123], v[122:123], v[122:123]
	v_pk_mul_f32 v[124:125], v[124:125], v[124:125]
	v_pk_mul_f32 v[126:127], v[126:127], v[126:127]
	v_pk_mul_f32 v[128:129], v[128:129], v[128:129]
	v_cvt_pk_bf16_f32 v122, v122, v123
	v_cvt_pk_bf16_f32 v123, v124, v125
	v_cvt_pk_bf16_f32 v124, v126, v127
	v_cvt_pk_bf16_f32 v125, v128, v129
	global_store_dwordx4 v[144:145], v[122:125], off
	s_nop 1
	v_max3_f32 v118, v118, v118, 0
	v_max3_f32 v119, v119, v119, 0
	v_max3_f32 v120, v120, v120, 0
	v_max3_f32 v121, v121, v121, 0
	v_max3_f32 v114, v114, v114, 0
	v_max3_f32 v115, v115, v115, 0
	v_max3_f32 v116, v116, v116, 0
	v_max3_f32 v117, v117, v117, 0
	v_pk_mul_f32 v[118:119], v[118:119], v[118:119]
	v_pk_mul_f32 v[120:121], v[120:121], v[120:121]
	v_pk_mul_f32 v[114:115], v[114:115], v[114:115]
	v_pk_mul_f32 v[116:117], v[116:117], v[116:117]
	v_cvt_pk_bf16_f32 v118, v118, v119
	v_cvt_pk_bf16_f32 v119, v120, v121
	v_cvt_pk_bf16_f32 v120, v114, v115
	v_cvt_pk_bf16_f32 v121, v116, v117
	global_store_dwordx4 v[144:145], v[118:121], off offset:256
	s_nop 1
	v_lshl_add_u64 v[114:115], v[144:145], 0, s[16:17]
	v_max3_f32 v110, v110, v110, 0
	v_max3_f32 v111, v111, v111, 0
	v_max3_f32 v112, v112, v112, 0
	v_max3_f32 v113, v113, v113, 0
	v_max3_f32 v106, v106, v106, 0
	v_max3_f32 v107, v107, v107, 0
	v_max3_f32 v108, v108, v108, 0
	v_max3_f32 v109, v109, v109, 0
	v_pk_mul_f32 v[110:111], v[110:111], v[110:111]
	v_pk_mul_f32 v[112:113], v[112:113], v[112:113]
	v_pk_mul_f32 v[106:107], v[106:107], v[106:107]
	v_pk_mul_f32 v[108:109], v[108:109], v[108:109]
	v_cvt_pk_bf16_f32 v110, v110, v111
	v_cvt_pk_bf16_f32 v111, v112, v113
	v_cvt_pk_bf16_f32 v112, v106, v107
	v_cvt_pk_bf16_f32 v113, v108, v109
	global_store_dwordx4 v[114:115], v[110:113], off
	s_nop 1
	v_max3_f32 v102, v102, v102, 0
	v_max3_f32 v103, v103, v103, 0
	v_max3_f32 v104, v104, v104, 0
	v_max3_f32 v105, v105, v105, 0
	v_max3_f32 v98, v98, v98, 0
	v_max3_f32 v99, v99, v99, 0
	v_max3_f32 v100, v100, v100, 0
	v_max3_f32 v101, v101, v101, 0
	v_pk_mul_f32 v[102:103], v[102:103], v[102:103]
	v_pk_mul_f32 v[104:105], v[104:105], v[104:105]
	v_pk_mul_f32 v[98:99], v[98:99], v[98:99]
	v_pk_mul_f32 v[100:101], v[100:101], v[100:101]
	v_cvt_pk_bf16_f32 v102, v102, v103
	v_cvt_pk_bf16_f32 v103, v104, v105
	v_cvt_pk_bf16_f32 v104, v98, v99
	v_cvt_pk_bf16_f32 v105, v100, v101
	global_store_dwordx4 v[114:115], v[102:105], off offset:256
	s_nop 1
	v_lshl_add_u64 v[98:99], v[114:115], 0, s[16:17]
	v_max3_f32 v94, v94, v94, 0
	v_max3_f32 v95, v95, v95, 0
	v_max3_f32 v96, v96, v96, 0
	v_max3_f32 v97, v97, v97, 0
	v_max3_f32 v90, v90, v90, 0
	v_max3_f32 v91, v91, v91, 0
	v_max3_f32 v92, v92, v92, 0
	v_max3_f32 v93, v93, v93, 0
	v_pk_mul_f32 v[94:95], v[94:95], v[94:95]
	v_pk_mul_f32 v[96:97], v[96:97], v[96:97]
	v_pk_mul_f32 v[90:91], v[90:91], v[90:91]
	v_pk_mul_f32 v[92:93], v[92:93], v[92:93]
	v_cvt_pk_bf16_f32 v94, v94, v95
	v_cvt_pk_bf16_f32 v95, v96, v97
	v_cvt_pk_bf16_f32 v96, v90, v91
	v_cvt_pk_bf16_f32 v97, v92, v93
	global_store_dwordx4 v[98:99], v[94:97], off
	s_nop 1
	v_max3_f32 v86, v86, v86, 0
	v_max3_f32 v87, v87, v87, 0
	v_max3_f32 v88, v88, v88, 0
	v_max3_f32 v89, v89, v89, 0
	v_max3_f32 v82, v82, v82, 0
	v_max3_f32 v83, v83, v83, 0
	v_max3_f32 v84, v84, v84, 0
	v_max3_f32 v85, v85, v85, 0
	v_pk_mul_f32 v[86:87], v[86:87], v[86:87]
	v_pk_mul_f32 v[88:89], v[88:89], v[88:89]
	v_pk_mul_f32 v[82:83], v[82:83], v[82:83]
	v_pk_mul_f32 v[84:85], v[84:85], v[84:85]
	v_cvt_pk_bf16_f32 v86, v86, v87
	v_cvt_pk_bf16_f32 v87, v88, v89
	v_cvt_pk_bf16_f32 v88, v82, v83
	v_cvt_pk_bf16_f32 v89, v84, v85
	global_store_dwordx4 v[98:99], v[86:89], off offset:256
	s_nop 1
	v_lshl_add_u64 v[82:83], v[98:99], 0, s[16:17]
	v_max3_f32 v78, v78, v78, 0
	v_max3_f32 v79, v79, v79, 0
	v_max3_f32 v80, v80, v80, 0
	v_max3_f32 v81, v81, v81, 0
	v_max3_f32 v74, v74, v74, 0
	v_max3_f32 v75, v75, v75, 0
	v_max3_f32 v76, v76, v76, 0
	v_max3_f32 v77, v77, v77, 0
	v_pk_mul_f32 v[78:79], v[78:79], v[78:79]
	v_pk_mul_f32 v[80:81], v[80:81], v[80:81]
	v_pk_mul_f32 v[74:75], v[74:75], v[74:75]
	v_pk_mul_f32 v[76:77], v[76:77], v[76:77]
	v_cvt_pk_bf16_f32 v78, v78, v79
	v_cvt_pk_bf16_f32 v79, v80, v81
	v_cvt_pk_bf16_f32 v80, v74, v75
	v_cvt_pk_bf16_f32 v81, v76, v77
	global_store_dwordx4 v[82:83], v[78:81], off
	s_nop 1
	v_max3_f32 v70, v70, v70, 0
	v_max3_f32 v71, v71, v71, 0
	v_max3_f32 v72, v72, v72, 0
	v_max3_f32 v73, v73, v73, 0
	v_max3_f32 v66, v66, v66, 0
	v_max3_f32 v67, v67, v67, 0
	v_max3_f32 v68, v68, v68, 0
	v_max3_f32 v69, v69, v69, 0
	v_pk_mul_f32 v[70:71], v[70:71], v[70:71]
	v_pk_mul_f32 v[72:73], v[72:73], v[72:73]
	v_pk_mul_f32 v[66:67], v[66:67], v[66:67]
	v_pk_mul_f32 v[68:69], v[68:69], v[68:69]
	v_cvt_pk_bf16_f32 v70, v70, v71
; __device__ __forceinline__ unsigned cvt_pk_bf16(float lo, float hi) { unsigned r; asm volatile("v_cvt_pk_bf16_f32 %0, %1, %2" : "=v"(r) : "v"(lo), "v"(hi)); return r; }
; #define PG8_OPQ(p) asm volatile("" : "+v"(p))
;     __device__ __forceinline__ void operator()(const f32x4 (&acc)[2][2][4][2], const Unit& u, int wr, int wc, int fr, int fq) const {
;     ...
;             for (int m = 0; m < 4; ++m) {
;                 PG8_OPQ(p);
; #pragma unroll
;                 for (int bj = 0; bj < 2; ++bj) { f32x4 v0 = acc[ai][bj][m][0], v1 = acc[ai][bj][m][1];
;                     if (ACT == 1) {
; #pragma unroll
;                         for (int j = 0; j < 4; ++j) { const float a0 = fmaxf(v0[j], 0.f), a1 = fmaxf(v1[j], 0.f); v0[j] = a0 * a0; v1[j] = a1 * a1; } }
;                     u32x4 w; w.x = cvt_pk_bf16(v0[0], v0[1]); w.y = cvt_pk_bf16(v0[2], v0[3]); w.z = cvt_pk_bf16(v1[0], v1[1]); w.w = cvt_pk_bf16(v1[2], v1[3]);
;                     *(u32x4*)(p + bj * HALF * 2) = w; }
;                 p += step;
;             }
;             p += 4 * step;
;         }
;     }
	v_cvt_pk_bf16_f32 v71, v72, v73
	v_cvt_pk_bf16_f32 v72, v66, v67
	v_cvt_pk_bf16_f32 v73, v68, v69
	global_store_dwordx4 v[82:83], v[70:73], off offset:256
	s_nop 1
	s_mov_b64 s[48:49], 0xa0000
	v_lshl_add_u64 v[66:67], v[82:83], 0, s[48:49]
	v_max3_f32 v62, v62, v62, 0
	v_max3_f32 v63, v63, v63, 0
	v_max3_f32 v64, v64, v64, 0
	v_max3_f32 v65, v65, v65, 0
	v_max3_f32 v58, v58, v58, 0
	v_max3_f32 v59, v59, v59, 0
	v_max3_f32 v60, v60, v60, 0
	v_max3_f32 v61, v61, v61, 0
	v_pk_mul_f32 v[62:63], v[62:63], v[62:63]
	v_pk_mul_f32 v[64:65], v[64:65], v[64:65]
	v_pk_mul_f32 v[58:59], v[58:59], v[58:59]
	v_pk_mul_f32 v[60:61], v[60:61], v[60:61]
	v_cvt_pk_bf16_f32 v62, v62, v63
	v_cvt_pk_bf16_f32 v63, v64, v65
	v_cvt_pk_bf16_f32 v64, v58, v59
	v_cvt_pk_bf16_f32 v65, v60, v61
	global_store_dwordx4 v[66:67], v[62:65], off
	s_nop 1
	v_max3_f32 v54, v54, v54, 0
	v_max3_f32 v55, v55, v55, 0
	v_max3_f32 v56, v56, v56, 0
	v_max3_f32 v57, v57, v57, 0
	v_max3_f32 v50, v50, v50, 0
	v_max3_f32 v51, v51, v51, 0
	v_max3_f32 v52, v52, v52, 0
	v_max3_f32 v53, v53, v53, 0
	v_pk_mul_f32 v[54:55], v[54:55], v[54:55]
	v_pk_mul_f32 v[56:57], v[56:57], v[56:57]
	v_pk_mul_f32 v[50:51], v[50:51], v[50:51]
	v_pk_mul_f32 v[52:53], v[52:53], v[52:53]
	v_cvt_pk_bf16_f32 v54, v54, v55
	v_cvt_pk_bf16_f32 v55, v56, v57
	v_cvt_pk_bf16_f32 v56, v50, v51
	v_cvt_pk_bf16_f32 v57, v52, v53
	global_store_dwordx4 v[66:67], v[54:57], off offset:256
	s_nop 1
	v_lshl_add_u64 v[50:51], v[66:67], 0, s[16:17]
	v_max3_f32 v46, v46, v46, 0
	v_max3_f32 v47, v47, v47, 0
	v_max3_f32 v48, v48, v48, 0
	v_max3_f32 v49, v49, v49, 0
	v_max3_f32 v42, v42, v42, 0
	v_max3_f32 v43, v43, v43, 0
	v_max3_f32 v44, v44, v44, 0
	v_max3_f32 v45, v45, v45, 0
	v_pk_mul_f32 v[46:47], v[46:47], v[46:47]
	v_pk_mul_f32 v[48:49], v[48:49], v[48:49]
	v_pk_mul_f32 v[42:43], v[42:43], v[42:43]
	v_pk_mul_f32 v[44:45], v[44:45], v[44:45]
	v_cvt_pk_bf16_f32 v46, v46, v47
	v_cvt_pk_bf16_f32 v47, v48, v49
	v_cvt_pk_bf16_f32 v48, v42, v43
	v_cvt_pk_bf16_f32 v49, v44, v45
	global_store_dwordx4 v[50:51], v[46:49], off
	s_nop 1
	v_max3_f32 v38, v38, v38, 0
	v_max3_f32 v39, v39, v39, 0
	v_max3_f32 v40, v40, v40, 0
	v_max3_f32 v41, v41, v41, 0
	v_max3_f32 v34, v34, v34, 0
	v_max3_f32 v35, v35, v35, 0
	v_max3_f32 v36, v36, v36, 0
	v_max3_f32 v37, v37, v37, 0
	v_pk_mul_f32 v[38:39], v[38:39], v[38:39]
	v_pk_mul_f32 v[40:41], v[40:41], v[40:41]
	v_pk_mul_f32 v[34:35], v[34:35], v[34:35]
	v_pk_mul_f32 v[36:37], v[36:37], v[36:37]
	v_cvt_pk_bf16_f32 v38, v38, v39
	v_cvt_pk_bf16_f32 v39, v40, v41
	v_cvt_pk_bf16_f32 v40, v34, v35
	v_cvt_pk_bf16_f32 v41, v36, v37
	global_store_dwordx4 v[50:51], v[38:41], off offset:256
	s_nop 1
	v_lshl_add_u64 v[34:35], v[50:51], 0, s[16:17]
	v_max3_f32 v30, v30, v30, 0
	v_max3_f32 v31, v31, v31, 0
	v_max3_f32 v32, v32, v32, 0
	v_max3_f32 v33, v33, v33, 0
	v_max3_f32 v26, v26, v26, 0
	v_max3_f32 v27, v27, v27, 0
	v_max3_f32 v28, v28, v28, 0
	v_max3_f32 v29, v29, v29, 0
	v_pk_mul_f32 v[30:31], v[30:31], v[30:31]
	v_pk_mul_f32 v[32:33], v[32:33], v[32:33]
	v_pk_mul_f32 v[26:27], v[26:27], v[26:27]
	v_pk_mul_f32 v[28:29], v[28:29], v[28:29]
	v_cvt_pk_bf16_f32 v30, v30, v31
	v_cvt_pk_bf16_f32 v31, v32, v33
	v_cvt_pk_bf16_f32 v32, v26, v27
	v_cvt_pk_bf16_f32 v33, v28, v29
	global_store_dwordx4 v[34:35], v[30:33], off
	s_nop 1
	v_max3_f32 v22, v22, v22, 0
	v_max3_f32 v23, v23, v23, 0
	v_max3_f32 v24, v24, v24, 0
	v_max3_f32 v25, v25, v25, 0
	v_max3_f32 v18, v18, v18, 0
	v_max3_f32 v19, v19, v19, 0
	v_max3_f32 v20, v20, v20, 0
	v_max3_f32 v21, v21, v21, 0
	v_pk_mul_f32 v[22:23], v[22:23], v[22:23]
	v_pk_mul_f32 v[24:25], v[24:25], v[24:25]
	v_pk_mul_f32 v[18:19], v[18:19], v[18:19]
	v_pk_mul_f32 v[20:21], v[20:21], v[20:21]
	v_cvt_pk_bf16_f32 v22, v22, v23
	v_cvt_pk_bf16_f32 v23, v24, v25
	v_cvt_pk_bf16_f32 v24, v18, v19
	v_cvt_pk_bf16_f32 v25, v20, v21
	global_store_dwordx4 v[34:35], v[22:25], off offset:256
	s_nop 1
	v_lshl_add_u64 v[18:19], v[34:35], 0, s[16:17]
	v_max3_f32 v14, v14, v14, 0
	v_max3_f32 v15, v15, v15, 0
	v_max3_f32 v16, v16, v16, 0
	v_max3_f32 v17, v17, v17, 0
	v_max3_f32 v10, v10, v10, 0
	v_max3_f32 v11, v11, v11, 0
	v_max3_f32 v12, v12, v12, 0
	v_max3_f32 v13, v13, v13, 0
	v_pk_mul_f32 v[14:15], v[14:15], v[14:15]
	v_pk_mul_f32 v[16:17], v[16:17], v[16:17]
	v_pk_mul_f32 v[10:11], v[10:11], v[10:11]
	v_pk_mul_f32 v[12:13], v[12:13], v[12:13]
	v_cvt_pk_bf16_f32 v14, v14, v15
	v_cvt_pk_bf16_f32 v15, v16, v17
	v_cvt_pk_bf16_f32 v16, v10, v11
	v_cvt_pk_bf16_f32 v17, v12, v13
	global_store_dwordx4 v[18:19], v[14:17], off
	s_nop 1
	v_max3_f32 v6, v6, v6, 0
	v_max3_f32 v7, v7, v7, 0
	v_max3_f32 v8, v8, v8, 0
	v_max3_f32 v9, v9, v9, 0
	v_max3_f32 v2, v2, v2, 0
	v_max3_f32 v3, v3, v3, 0
	v_max3_f32 v4, v4, v4, 0
	v_max3_f32 v5, v5, v5, 0
	v_pk_mul_f32 v[6:7], v[6:7], v[6:7]
	v_pk_mul_f32 v[8:9], v[8:9], v[8:9]
	v_pk_mul_f32 v[2:3], v[2:3], v[2:3]
	v_pk_mul_f32 v[4:5], v[4:5], v[4:5]
	v_cvt_pk_bf16_f32 v6, v6, v7
	v_cvt_pk_bf16_f32 v7, v8, v9
	v_cvt_pk_bf16_f32 v8, v2, v3
	v_cvt_pk_bf16_f32 v9, v4, v5
	global_store_dwordx4 v[18:19], v[6:9], off offset:256
	s_nop 1
	s_cmp_eq_u32 s8, 15
	s_mov_b64 s[8:9], -1
	s_cbranch_scc1 .LBB0_430
	s_andn2_b64 vcc, exec, s[38:39]
	s_cbranch_vccnz .LBB0_429
	s_branch .LBB0_429
